# P13 final RMSNorm: gain vector loaded once per wave before the row loop (was 8 waited L2 round trips per row that also drained the stores); on top of mnk + saddr
# speedup vs baseline: 1.0014x; 1.0014x over previous
.LBB0_2878:
	s_cmp_lt_i32 s56, 14
	s_cselect_b64 s[2:3], -1, 0
	s_and_b64 s[0:1], s[2:3], s[0:1]
	s_andn2_b64 vcc, exec, s[0:1]
	s_cbranch_vccnz .LBB0_2884
	v_mov_b32_e32 v0, 0x4000
	v_mov_b32_e32 v1, 0x7000
	s_waitcnt vmcnt(0)
	v_mov_b32_e32 v2, 0xa000
	s_waitcnt lgkmcnt(0)
	v_mov_b32_e32 v3, 0xe000
	v_mov_b32_e32 v4, 0x11000
	v_mov_b32_e32 v5, 0x15000
	v_mov_b32_e32 v6, 0x18000
	v_mov_b32_e32 v7, 0x1b000
	v_mov_b32_e32 v8, 0x1f000
	v_mov_b32_e32 v9, 0x22000
	v_mov_b32_e32 v10, 0x25000
	v_mov_b32_e32 v11, 0x29000
	v_mov_b32_e32 v12, 0x2c000
	v_mov_b32_e32 v13, 0x30000
	global_load_dword v0, v0, s[54:55] offset:512 sc1
	s_cmpk_gt_i32 s34, 0x3fff
	global_load_dword v1, v1, s[54:55] offset:2048 sc1
	s_nop 0
	global_load_dword v2, v2, s[54:55] offset:3584 sc1
	s_nop 0
	global_load_dword v3, v3, s[54:55] offset:1024 sc1
	s_nop 0
	global_load_dword v4, v4, s[54:55] offset:2560 sc1
	s_nop 0
	global_load_dword v5, v5, s[54:55] sc1
	s_nop 0
	global_load_dword v6, v6, s[54:55] offset:1536 sc1
	s_nop 0
	global_load_dword v7, v7, s[54:55] offset:3072 sc1
	s_nop 0
	global_load_dword v8, v8, s[54:55] offset:512 sc1
	s_nop 0
	global_load_dword v9, v9, s[54:55] offset:2048 sc1
	s_nop 0
	global_load_dword v10, v10, s[54:55] offset:3584 sc1
	s_nop 0
	global_load_dword v11, v11, s[54:55] offset:1024 sc1
	s_nop 0
	global_load_dword v12, v12, s[54:55] offset:2560 sc1
	s_nop 0
	global_load_dword v13, v13, s[54:55] sc1
	s_cbranch_scc1 .LBB0_2884
	s_waitcnt vmcnt(12)
	v_or_b32_e32 v0, v0, v1
	s_waitcnt vmcnt(11)
	v_or_b32_e32 v0, v0, v2
	s_waitcnt vmcnt(10)
	v_or_b32_e32 v0, v0, v3
	s_waitcnt vmcnt(9)
	v_or_b32_e32 v0, v0, v4
	s_waitcnt vmcnt(8)
	v_or_b32_e32 v0, v0, v5
	s_waitcnt vmcnt(7)
	v_or_b32_e32 v0, v0, v6
	s_waitcnt vmcnt(6)
	v_or_b32_e32 v0, v0, v7
	s_waitcnt vmcnt(5)
	v_or_b32_e32 v0, v0, v8
	s_waitcnt vmcnt(4)
	v_or_b32_e32 v0, v0, v9
	s_waitcnt vmcnt(3)
	v_or_b32_e32 v0, v0, v10
	s_waitcnt vmcnt(2)
	v_or_b32_e32 v0, v0, v11
	s_waitcnt vmcnt(1)
	v_or_b32_e32 v0, v0, v12
	s_waitcnt vmcnt(0)
	v_or_b32_e32 v4, v0, v13
	v_lshlrev_b32_e32 v0, 5, v182
	v_mov_b32_e32 v1, 0
	v_lshl_add_u64 v[32:33], s[30:31], 0, v[0:1]
	s_mov_b64 s[0:1], 0x1000
	v_lshl_add_u64 v[34:35], v[32:33], 0, s[0:1]
	s_mov_b64 s[0:1], 0x1800
	v_lshl_add_u64 v[36:37], v[32:33], 0, s[0:1]
	s_mov_b64 s[0:1], 0x2000
	v_lshl_add_u64 v[38:39], v[32:33], 0, s[0:1]
	s_mov_b64 s[0:1], 0x2800
	v_lshl_add_u64 v[40:41], v[32:33], 0, s[0:1]
	s_mov_b64 s[0:1], 0x3000
	v_lshl_add_u64 v[42:43], v[32:33], 0, s[0:1]
	s_mov_b64 s[0:1], 0x3800
	s_ashr_i32 s35, s34, 31
	v_lshl_add_u64 v[44:45], v[32:33], 0, s[0:1]
	s_lshl_b64 s[0:1], s[34:35], 14
	s_add_u32 s0, s52, s0
	s_addc_u32 s1, s53, s1
	v_lshl_add_u64 v[2:3], s[0:1], 0, v[0:1]
	s_mov_b64 s[0:1], 0x3810
	s_ashr_i32 s59, s58, 31
	v_lshl_add_u64 v[46:47], v[2:3], 0, s[0:1]
	s_lshl_b64 s[4:5], s[58:59], 14
	s_lshl_b64 s[0:1], s[34:35], 13
	s_add_u32 s0, s54, s0
	v_lshlrev_b32_e32 v0, 4, v182
	s_addc_u32 s1, s55, s1
	v_lshl_add_u64 v[0:1], s[0:1], 0, v[0:1]
	s_mov_b64 s[0:1], 0x30701c00
	v_cmp_eq_u32_e32 vcc, 0, v4
	v_lshl_add_u64 v[48:49], v[0:1], 0, s[0:1]
	s_lshl_b64 s[6:7], s[58:59], 13
	v_cndmask_b32_e64 v0, 0, 1, vcc
	v_cmp_ne_u32_e64 s[0:1], 1, v0
	v_mbcnt_lo_u32_b32 v0, -1, 0
	s_movk_i32 s8, 0xf000
	v_mov_b32_e32 v67, 0x358637bd
	s_mov_b32 s9, 0xf800000
	v_mov_b32_e32 v84, 0x260
	s_movk_i32 s10, 0xd000
	s_movk_i32 s11, 0xe000
	v_mbcnt_hi_u32_b32 v85, -1, v0
	global_load_dwordx4 v[100:103], v[32:33], off
	global_load_dwordx4 v[104:107], v[32:33], off offset:16
	global_load_dwordx4 v[108:111], v[32:33], off offset:2048
	global_load_dwordx4 v[112:115], v[32:33], off offset:2064
	global_load_dwordx4 v[116:119], v[34:35], off
	global_load_dwordx4 v[120:123], v[34:35], off offset:16
	global_load_dwordx4 v[124:127], v[36:37], off
	global_load_dwordx4 v[128:131], v[36:37], off offset:16
	global_load_dwordx4 v[132:135], v[38:39], off
	global_load_dwordx4 v[136:139], v[38:39], off offset:16
	global_load_dwordx4 v[140:143], v[40:41], off
	global_load_dwordx4 v[144:147], v[40:41], off offset:16
	global_load_dwordx4 v[148:151], v[42:43], off
	global_load_dwordx4 v[152:155], v[42:43], off offset:16
	global_load_dwordx4 v[156:159], v[44:45], off
	global_load_dwordx4 v[160:163], v[44:45], off offset:16
	s_waitcnt vmcnt(0)
	s_branch .LBB0_2882
.LBB0_2881:
	v_pk_mul_f32 v[94:95], v[66:67], v[80:81] op_sel_hi:[0,1]
	v_pk_mul_f32 v[80:81], v[66:67], v[82:83] op_sel_hi:[0,1]
	v_and_b32_e32 v31, 0xffff0000, v31
	v_add_co_u32_e32 v96, vcc, s10, v46
	v_pk_mul_f32 v[82:83], v[66:67], v[78:79] op_sel_hi:[0,1]
	s_nop 0
	v_addc_co_u32_e32 v97, vcc, -1, v47, vcc
	v_pk_mul_f32 v[30:31], v[66:67], v[30:31] op_sel_hi:[0,1]
	v_and_b32_e32 v27, 0xffff0000, v27
	v_pk_mul_f32 v[26:27], v[66:67], v[26:27] op_sel_hi:[0,1]
	v_and_b32_e32 v23, 0xffff0000, v23
	v_pk_mul_f32 v[22:23], v[66:67], v[22:23] op_sel_hi:[0,1]
	v_pk_mul_f32 v[20:21], v[66:67], v[20:21] op_sel_hi:[0,1]
	v_and_b32_e32 v19, 0xffff0000, v19
	v_and_b32_e32 v15, 0xffff0000, v15
	v_pk_mul_f32 v[14:15], v[66:67], v[14:15] op_sel_hi:[0,1]
	v_and_b32_e32 v11, 0xffff0000, v11
	v_pk_mul_f32 v[10:11], v[66:67], v[10:11] op_sel_hi:[0,1]
	v_and_b32_e32 v7, 0xffff0000, v7
	v_pk_mul_f32 v[6:7], v[66:67], v[6:7] op_sel_hi:[0,1]
	v_pk_mul_f32 v[4:5], v[66:67], v[4:5] op_sel_hi:[0,1]
	v_and_b32_e32 v3, 0xffff0000, v3
	s_add_i32 s34, s34, s58
	s_cmpk_lt_i32 s34, 0x4000
	v_lshl_add_u64 v[48:49], v[48:49], 0, s[6:7]
	v_pk_mul_f32 v[80:81], v[80:81], v[102:103]
	v_pk_mul_f32 v[78:79], v[94:95], v[100:101]
	v_pk_mul_f32 v[88:89], v[30:31], v[106:107]
	v_pk_mul_f32 v[86:87], v[82:83], v[104:105]
	global_store_dwordx4 v[96:97], v[78:81], off offset:-2064
	global_store_dwordx4 v[96:97], v[86:89], off offset:-2048
	v_pk_mul_f32 v[30:31], v[66:67], v[74:75] op_sel_hi:[0,1]
	v_pk_mul_f32 v[74:75], v[66:67], v[76:77] op_sel_hi:[0,1]
	v_pk_mul_f32 v[76:77], v[66:67], v[72:73] op_sel_hi:[0,1]
	v_add_co_u32_e32 v82, vcc, s11, v46
	v_pk_mul_f32 v[74:75], v[74:75], v[110:111]
	v_pk_mul_f32 v[72:73], v[30:31], v[108:109]
	v_addc_co_u32_e32 v83, vcc, -1, v47, vcc
	v_pk_mul_f32 v[78:79], v[26:27], v[114:115]
	v_pk_mul_f32 v[76:77], v[76:77], v[112:113]
	global_store_dwordx4 v[96:97], v[72:75], off offset:-16
	global_store_dwordx4 v[82:83], v[76:79], off offset:-4096
	v_pk_mul_f32 v[26:27], v[66:67], v[68:69] op_sel_hi:[0,1]
	v_pk_mul_f32 v[30:31], v[66:67], v[70:71] op_sel_hi:[0,1]
	v_pk_mul_f32 v[68:69], v[66:67], v[28:29] op_sel_hi:[0,1]
	v_pk_mul_f32 v[28:29], v[30:31], v[118:119]
	v_pk_mul_f32 v[26:27], v[26:27], v[116:117]
	v_pk_mul_f32 v[70:71], v[22:23], v[122:123]
	v_pk_mul_f32 v[68:69], v[68:69], v[120:121]
	global_store_dwordx4 v[82:83], v[26:29], off offset:-2064
	global_store_dwordx4 v[82:83], v[68:71], off offset:-2048
	v_pk_mul_f32 v[22:23], v[66:67], v[24:25] op_sel_hi:[0,1]
	v_pk_mul_f32 v[24:25], v[66:67], v[16:17] op_sel_hi:[0,1]
	v_pk_mul_f32 v[30:31], v[66:67], v[18:19] op_sel_hi:[0,1]
	v_pk_mul_f32 v[18:19], v[22:23], v[126:127]
	v_pk_mul_f32 v[16:17], v[20:21], v[124:125]
	v_pk_mul_f32 v[22:23], v[30:31], v[130:131]
	v_pk_mul_f32 v[20:21], v[24:25], v[128:129]
	global_store_dwordx4 v[82:83], v[16:19], off offset:-16
	global_store_dwordx4 v[82:83], v[20:23], off
	v_pk_mul_f32 v[24:25], v[66:67], v[62:63] op_sel_hi:[0,1]
	v_pk_mul_f32 v[26:27], v[66:67], v[64:65] op_sel_hi:[0,1]
	v_add_co_u32_e32 v30, vcc, s8, v46
	v_pk_mul_f32 v[28:29], v[66:67], v[60:61] op_sel_hi:[0,1]
	s_nop 0
	v_addc_co_u32_e32 v31, vcc, -1, v47, vcc
	v_pk_mul_f32 v[18:19], v[26:27], v[134:135]
	v_pk_mul_f32 v[16:17], v[24:25], v[132:133]
	v_pk_mul_f32 v[22:23], v[14:15], v[138:139]
	v_pk_mul_f32 v[20:21], v[28:29], v[136:137]
	global_store_dwordx4 v[30:31], v[16:19], off offset:-2064
	global_store_dwordx4 v[30:31], v[20:23], off offset:-2048
	s_nop 1
	v_pk_mul_f32 v[22:23], v[66:67], v[56:57] op_sel_hi:[0,1]
	v_pk_mul_f32 v[24:25], v[66:67], v[58:59] op_sel_hi:[0,1]
	v_pk_mul_f32 v[26:27], v[66:67], v[54:55] op_sel_hi:[0,1]
	v_pk_mul_f32 v[16:17], v[24:25], v[142:143]
	v_pk_mul_f32 v[14:15], v[22:23], v[140:141]
	v_pk_mul_f32 v[20:21], v[10:11], v[146:147]
	v_pk_mul_f32 v[18:19], v[26:27], v[144:145]
	global_store_dwordx4 v[30:31], v[14:17], off offset:-16
	global_store_dwordx4 v[46:47], v[18:21], off offset:-4096
	v_pk_mul_f32 v[10:11], v[66:67], v[50:51] op_sel_hi:[0,1]
	v_pk_mul_f32 v[22:23], v[66:67], v[52:53] op_sel_hi:[0,1]
	v_pk_mul_f32 v[24:25], v[66:67], v[12:13] op_sel_hi:[0,1]
	v_pk_mul_f32 v[12:13], v[22:23], v[150:151]
	v_pk_mul_f32 v[10:11], v[10:11], v[148:149]
	v_pk_mul_f32 v[16:17], v[6:7], v[154:155]
	v_pk_mul_f32 v[14:15], v[24:25], v[152:153]
	global_store_dwordx4 v[46:47], v[10:13], off offset:-2064
	global_store_dwordx4 v[46:47], v[14:17], off offset:-2048
	v_pk_mul_f32 v[6:7], v[66:67], v[8:9] op_sel_hi:[0,1]
	v_pk_mul_f32 v[8:9], v[66:67], v[0:1] op_sel_hi:[0,1]
	v_pk_mul_f32 v[18:19], v[66:67], v[2:3] op_sel_hi:[0,1]
	v_pk_mul_f32 v[2:3], v[6:7], v[158:159]
	v_pk_mul_f32 v[0:1], v[4:5], v[156:157]
	v_pk_mul_f32 v[6:7], v[18:19], v[162:163]
	v_pk_mul_f32 v[4:5], v[8:9], v[160:161]
	global_store_dwordx4 v[46:47], v[0:3], off offset:-16
	global_store_dwordx4 v[46:47], v[4:7], off
	v_lshl_add_u64 v[46:47], v[46:47], 0, s[4:5]
	s_cbranch_scc0 .LBB0_2884
